# attention combine pass L3: same O1/O2 load hoisting as L0
# speedup vs baseline: 1.0045x; 1.0045x over previous
; #define GAS __attribute__((address_space(1)))
; #define LAS __attribute__((address_space(3)))
;     __device__ __forceinline__ void ids() { lane = fresh_lane(); tid = wave * 64 + lane; }
; __device__ __forceinline__ void unpack8(const v4u w, float (&f)[8]) { f[0] = bfl(w.x); f[1] = bfh(w.x); f[2] = bfl(w.y); f[3] = bfh(w.y); f[4] = bfl(w.z); f[5] = bfh(w.z); f[6] = bfl(w.w); f[7] = bfh(w.w); }
; __device__ __forceinline__ v4u pack8(const float (&f)[8]) { v4u w; w.x = pk2(f[0], f[1]); w.y = pk2(f[2], f[3]); w.z = pk2(f[4], f[5]); w.w = pk2(f[6], f[7]); return w; }
; template <bool COMBINE>
; __device__ __forceinline__ void attn_phase(Frame& F, const bf16* QKV, bf16* O12, float* LSE, bf16* MO) {
;     F.ids();
;     const unsigned ldsb = (unsigned)(size_t)F.lds;
;     const int nunits = COMBINE ? NB * 16 * 8 : NB * 2 * 16 * 8;
;     for (int u = F.vcu; u < nunits; u += F.G) {
;         F.ids();
;         const int lane = F.lane, ql = lane & 31, hh = lane >> 5;
;         const int qblk = u & 7, h = (u >> 3) & 15, rest = u >> 7;
;         const int gg = COMBINE ? 0 : 1 + (rest & 1), b = COMBINE ? rest : (rest >> 1);
;         const int Lsh = gg == 0 ? 11 : (gg == 1 ? 9 : 7);
;         const int q0 = qblk * 256, cs0 = (q0 >> Lsh) << Lsh, kv0 = (q0 - 128) > cs0 ? (q0 - 128) : cs0;
;         const bf16* Qp = QKV + (size_t)gg * 6144 + h * 128; const bf16* Kp = Qp + 2048; const bf16* Vp = Qp + 4096;
;         const int qw0 = q0 + 32 * F.wave, cs = (qw0 >> Lsh) << Lsh;
;         const int qrow = tokrow(b, qw0 + ql, Lsh);
;     ...
;         for (int i = 0; i < 8; ++i) { const int ci = i * 64 + lane, row = ci >> 4, ch = ci & 15;
;             const v4u t = *(const LAS v4u*)(stg + row * SROW + ch * 16);
;             const size_t go = (size_t)tokrow(b, qw0 + row, Lsh) * D + h * 128 + ch * 8;
;             if (!COMBINE) *(GAS v4u*)(O12 + (size_t)(gg - 1) * M * D + go) = t;
;             else { const f32x4 wt = *(const LAS f32x4*)(stg + 32 * SROW + row * 16);
;                 const v4u a = *(const GAS v4u*)(O12 + go), bq = *(const GAS v4u*)(O12 + (size_t)M * D + go);
;                 float f0[8], f1[8], f2[8], r[8]; unpack8(t, f0); unpack8(a, f1); unpack8(bq, f2);
; #pragma unroll
;                 for (int jj = 0; jj < 8; ++jj) r[jj] = wt[0] * f0[jj] + wt[1] * f1[jj] + wt[2] * f2[jj];
;                 *(GAS v4u*)(MO + go) = pack8(r); }
.LBB0_3558:
	s_cmp_gt_i32 s56, 34
	s_cselect_b64 s[0:1], -1, 0
	s_cmp_lt_i32 s57, 35
	s_cselect_b64 s[4:5], -1, 0
	s_or_b64 s[0:1], s[0:1], s[4:5]
	s_and_b64 vcc, exec, s[0:1]
	s_cbranch_vccnz .LBB0_3697
	s_add_i32 s0, 0, 0x20520
	v_mov_b32_e32 v0, s0
	s_waitcnt lgkmcnt(0)
	ds_read_b64 v[0:1], v0
	s_mov_b32 s36, 0
	s_cmpk_gt_i32 s96, 0x1ff
	s_waitcnt lgkmcnt(0)
	v_readfirstlane_b32 s4, v0
	v_readfirstlane_b32 s5, v1
	v_mbcnt_lo_u32_b32 v0, -1, 0
	v_mbcnt_hi_u32_b32 v0, -1, v0
	s_cbranch_scc1 .LBB0_3643
	s_add_u32 s3, s4, 0x30500000
	s_addc_u32 s53, s5, 0
	s_add_u32 s0, s4, 0x42500000
	s_addc_u32 s1, s5, 0
	s_add_u32 s60, s4, 0x46500000
	s_addc_u32 s61, s5, 0
	s_add_u32 s62, s4, 0x2e500000
	s_addc_u32 s63, s5, 0
	s_add_u32 s64, s4, 0x44500000
	v_readlane_b32 s4, v246, 6
	s_addc_u32 s65, s5, 0
	s_lshl_b32 s55, s4, 5
	s_mulk_i32 s4, 0x2400
	s_add_i32 s77, s4, 0
	v_readlane_b32 s4, v246, 4
	v_mbcnt_lo_u32_b32 v0, -1, 0
	s_or_b32 s70, s55, 16
	s_add_i32 s71, s55, 32
	s_add_i32 s74, s55, 64
	s_add_i32 s75, s55, 0x60
	s_add_i32 s76, s55, 0x80
	s_lshl_b32 s78, s4, 4
	s_lshl_b32 s79, s52, 4
	s_lshl_b32 s80, s4, 8
	s_lshl_b32 s81, s52, 8
	v_mov_b32_e32 v194, 0x80
	v_mov_b32_e32 v189, 0
	s_mov_b32 s82, 0x9000
	s_movk_i32 s83, 0x140
	s_mov_b32 s84, 0x42400000
	s_mov_b32 s85, 0xc2fc0000
	v_mbcnt_hi_u32_b32 v195, -1, v0
	v_mov_b32_e32 v196, 0x42800000
	v_mov_b32_e32 v197, 0xf149f2ca
	s_mov_b32 s86, 0x41300000
	s_mov_b32 s87, 0x41800000
	s_mov_b32 s88, 0x41880000
	s_mov_b32 s89, 0x41900000
	s_mov_b32 s90, 0x41980000
	s_mov_b32 s91, 0x41c00000
	s_mov_b32 s92, 0x41c80000
	s_mov_b32 s93, 0x41d00000
	s_mov_b32 s94, 0x41d80000
	s_add_i32 s95, 0, 0x3c00
	s_add_i32 s96, 0, 0x6400
	s_add_i32 s97, 0, 0x8c00
	s_add_i32 s58, 0, 0xb400
	s_movk_i32 s59, 0x110
	s_mov_b32 s34, s4
	s_mov_b64 s[66:67], 0x2000
	v_readlane_b32 s5, v246, 5
	s_branch .LBB0_3562
.LBB0_3561:
	s_or_b64 exec, exec, s[4:5]
	v_ashrrev_i32_e32 v10, 4, v198
	v_add_u32_e32 v0, s54, v10
	v_and_b32_e32 v1, 0x7ff, v0
	v_ashrrev_i32_e32 v0, 11, v0
	v_add3_u32 v0, v0, s35, v1
	v_ashrrev_i32_e32 v1, 31, v0
	v_lshlrev_b64 v[18:19], 12, v[0:1]
	v_lshl_or_b32 v1, s6, 1, v188
	v_or_b32_e32 v18, v18, v1
	s_waitcnt lgkmcnt(0)
	v_lshl_add_u64 v[6:7], s[0:1], 0, v[18:19]
	v_lshl_add_u64 v[2:3], s[64:65], 0, v[18:19]
	global_load_dwordx4 v[64:67], v18, s[64:65]
	global_load_dwordx4 v[68:71], v18, s[0:1]
	s_add_u32 vcc_lo, s64, 0x4000
	s_addc_u32 vcc_hi, s65, 0
	global_load_dwordx4 v[72:75], v18, vcc
	s_add_u32 s4, s0, 0x4000
	s_addc_u32 s5, s1, 0
	global_load_dwordx4 v[76:79], v18, s[4:5]
	s_add_u32 vcc_lo, s64, 0x8000
	s_addc_u32 vcc_hi, s65, 0
	global_load_dwordx4 v[80:83], v18, vcc
	s_add_u32 s4, s0, 0x8000
	s_addc_u32 s5, s1, 0
	global_load_dwordx4 v[84:87], v18, s[4:5]
	s_add_u32 vcc_lo, s64, 0xc000
	s_addc_u32 vcc_hi, s65, 0
	global_load_dwordx4 v[88:91], v18, vcc
	s_add_u32 s4, s0, 0xc000
	s_addc_u32 s5, s1, 0
	global_load_dwordx4 v[92:95], v18, s[4:5]
	s_add_u32 vcc_lo, s64, 0x10000
	s_addc_u32 vcc_hi, s65, 0
	global_load_dwordx4 v[96:99], v18, vcc
	s_add_u32 s4, s0, 0x10000
	s_addc_u32 s5, s1, 0
	global_load_dwordx4 v[100:103], v18, s[4:5]
	s_add_u32 vcc_lo, s64, 0x14000
	s_addc_u32 vcc_hi, s65, 0
	global_load_dwordx4 v[104:107], v18, vcc
	s_add_u32 s4, s0, 0x14000
	s_addc_u32 s5, s1, 0
	global_load_dwordx4 v[108:111], v18, s[4:5]
	s_add_u32 vcc_lo, s64, 0x18000
	s_addc_u32 vcc_hi, s65, 0
	global_load_dwordx4 v[112:115], v18, vcc
	s_add_u32 s4, s0, 0x18000
	s_addc_u32 s5, s1, 0
	global_load_dwordx4 v[116:119], v18, s[4:5]
	s_add_u32 vcc_lo, s64, 0x1c000
	s_addc_u32 vcc_hi, s65, 0
	global_load_dwordx4 v[120:123], v18, vcc
	s_add_u32 s4, s0, 0x1c000
	s_addc_u32 s5, s1, 0
	global_load_dwordx4 v[124:127], v18, s[4:5]
	v_add_u32_e32 v0, s77, v188
	v_and_b32_e32 v12, -16, v198
	v_mad_u64_u32 v[10:11], s[4:5], v10, s59, v[0:1]
	v_add_u32_e32 v14, s77, v12
	ds_read_b128 v[10:13], v10
	ds_read_b128 v[14:17], v14 offset:8704
	v_add_u32_e32 v32, 64, v198
	v_ashrrev_i32_e32 v33, 4, v32
	s_waitcnt lgkmcnt(0)
	v_add_u32_e32 v17, s54, v33
	v_and_b32_e32 v20, 0x7ff, v17
	v_ashrrev_i32_e32 v17, 11, v17
	v_add3_u32 v20, v17, s35, v20
	v_lshlrev_b32_e32 v34, 16, v10
	v_and_b32_e32 v35, 0xffff0000, v10
	v_lshlrev_b32_e32 v36, 16, v11
	v_and_b32_e32 v37, 0xffff0000, v11
	v_mov_b32_e32 v10, v15
	v_mov_b32_e32 v11, v16
	v_ashrrev_i32_e32 v21, 31, v20
	v_and_b32_e32 v41, 0xffff0000, v13
	v_lshlrev_b64 v[20:21], 12, v[20:21]
	v_lshlrev_b32_e32 v38, 16, v12
	v_and_b32_e32 v39, 0xffff0000, v12
	v_lshlrev_b32_e32 v40, 16, v13
	v_lshl_add_u64 v[12:13], s[62:63], 0, v[18:19]
	v_or_b32_e32 v20, v20, v1
	v_lshl_add_u64 v[18:19], s[64:65], 0, v[20:21]
	v_lshl_add_u64 v[16:17], s[0:1], 0, v[20:21]
	s_add_i32 s34, s34, s52
	s_add_i32 s78, s78, s79
	s_add_i32 s80, s80, s81
	s_cmpk_lt_i32 s34, 0x200
	s_waitcnt vmcnt(14)
; #define GAS __attribute__((address_space(1)))
; #define LAS __attribute__((address_space(3)))
; __device__ __forceinline__ void unpack8(const v4u w, float (&f)[8]) { f[0] = bfl(w.x); f[1] = bfh(w.x); f[2] = bfl(w.y); f[3] = bfh(w.y); f[4] = bfl(w.z); f[5] = bfh(w.z); f[6] = bfl(w.w); f[7] = bfh(w.w); }
; __device__ __forceinline__ v4u pack8(const float (&f)[8]) { v4u w; w.x = pk2(f[0], f[1]); w.y = pk2(f[2], f[3]); w.z = pk2(f[4], f[5]); w.w = pk2(f[6], f[7]); return w; }
; template <bool COMBINE>
; __device__ __forceinline__ void attn_phase(Frame& F, const bf16* QKV, bf16* O12, float* LSE, bf16* MO) {
;     ...
;         for (int i = 0; i < 8; ++i) { const int ci = i * 64 + lane, row = ci >> 4, ch = ci & 15;
;             const v4u t = *(const LAS v4u*)(stg + row * SROW + ch * 16);
;             const size_t go = (size_t)tokrow(b, qw0 + row, Lsh) * D + h * 128 + ch * 8;
;             if (!COMBINE) *(GAS v4u*)(O12 + (size_t)(gg - 1) * M * D + go) = t;
;             else { const f32x4 wt = *(const LAS f32x4*)(stg + 32 * SROW + row * 16);
;                 const v4u a = *(const GAS v4u*)(O12 + go), bq = *(const GAS v4u*)(O12 + (size_t)M * D + go);
;                 float f0[8], f1[8], f2[8], r[8]; unpack8(t, f0); unpack8(a, f1); unpack8(bq, f2);
; #pragma unroll
;                 for (int jj = 0; jj < 8; ++jj) r[jj] = wt[0] * f0[jj] + wt[1] * f1[jj] + wt[2] * f2[jj];
;                 *(GAS v4u*)(MO + go) = pack8(r); }
	v_mov_b32_e32 v2, v64
	v_mov_b32_e32 v3, v65
	v_mov_b32_e32 v4, v66
	v_mov_b32_e32 v5, v67
	v_mov_b32_e32 v6, v68
	v_mov_b32_e32 v7, v69
	v_mov_b32_e32 v8, v70
	v_mov_b32_e32 v9, v71
	v_lshlrev_b32_e32 v23, 16, v2
	v_and_b32_e32 v25, 0xffff0000, v2
	v_lshlrev_b32_e32 v27, 16, v3
	v_lshlrev_b32_e32 v26, 16, v7
	v_and_b32_e32 v3, 0xffff0000, v3
	v_and_b32_e32 v2, 0xffff0000, v7
	v_lshlrev_b32_e32 v7, 16, v4
	v_and_b32_e32 v29, 0xffff0000, v4
	v_lshlrev_b32_e32 v31, 16, v5
	v_and_b32_e32 v5, 0xffff0000, v5
	v_and_b32_e32 v4, 0xffff0000, v9
	v_lshlrev_b32_e32 v22, 16, v6
	v_and_b32_e32 v24, 0xffff0000, v6
	v_lshlrev_b32_e32 v6, 16, v8
	v_and_b32_e32 v28, 0xffff0000, v8
	v_lshlrev_b32_e32 v30, 16, v9
	v_pk_mul_f32 v[2:3], v[10:11], v[2:3]
	v_pk_mul_f32 v[4:5], v[10:11], v[4:5]
	v_pk_mul_f32 v[8:9], v[10:11], v[22:23]
	v_pk_mul_f32 v[22:23], v[10:11], v[24:25]
	v_pk_mul_f32 v[24:25], v[10:11], v[26:27]
	v_pk_mul_f32 v[6:7], v[10:11], v[6:7]
	v_pk_mul_f32 v[26:27], v[10:11], v[28:29]
	v_pk_mul_f32 v[28:29], v[10:11], v[30:31]
	v_fma_f32 v2, v14, v37, v2
	v_fma_f32 v4, v14, v41, v4
	v_fma_f32 v8, v14, v34, v8
	v_fma_f32 v10, v14, v35, v22
	v_fma_f32 v11, v14, v36, v24
	v_fma_f32 v6, v14, v38, v6
	v_fma_f32 v15, v14, v39, v26
	v_fma_f32 v22, v14, v40, v28
	v_add_f32_e32 v3, v2, v3
	v_add_f32_e32 v5, v4, v5
	v_add_f32_e32 v8, v8, v9
	v_add_f32_e32 v9, v10, v23
	v_add_f32_e32 v10, v11, v25
	v_add_f32_e32 v6, v6, v7
	v_add_f32_e32 v7, v15, v27
	v_add_f32_e32 v11, v22, v29
	v_cvt_pk_bf16_f32 v2, v8, v9
	v_cvt_pk_bf16_f32 v3, v10, v3
	v_cvt_pk_bf16_f32 v4, v6, v7
	v_cvt_pk_bf16_f32 v5, v11, v5
	global_store_dwordx4 v[12:13], v[2:5], off
	v_and_b32_e32 v12, -16, v32
	v_mad_u64_u32 v[10:11], s[4:5], v33, s59, v[0:1]
	v_add_u32_e32 v14, s77, v12
	ds_read_b128 v[10:13], v10
	ds_read_b128 v[14:17], v14 offset:8704
	v_add_u32_e32 v34, 0x80, v198
	v_ashrrev_i32_e32 v32, 4, v34
	v_add_u32_e32 v18, s54, v32
	s_waitcnt lgkmcnt(0)
	v_and_b32_e32 v17, 0x7ff, v18
	v_ashrrev_i32_e32 v18, 11, v18
	v_add3_u32 v18, v18, s35, v17
	v_lshlrev_b32_e32 v33, 16, v10
	v_and_b32_e32 v35, 0xffff0000, v10
	v_lshlrev_b32_e32 v36, 16, v11
	v_and_b32_e32 v37, 0xffff0000, v11
	v_mov_b32_e32 v10, v15
	v_mov_b32_e32 v11, v16
	v_ashrrev_i32_e32 v19, 31, v18
	v_and_b32_e32 v41, 0xffff0000, v13
	v_lshlrev_b64 v[18:19], 12, v[18:19]
	v_lshlrev_b32_e32 v38, 16, v12
	v_and_b32_e32 v39, 0xffff0000, v12
	v_lshlrev_b32_e32 v40, 16, v13
	v_or_b32_e32 v18, v18, v1
	v_lshl_add_u64 v[12:13], s[62:63], 0, v[20:21]
	v_lshl_add_u64 v[20:21], s[64:65], 0, v[18:19]
	v_lshl_add_u64 v[16:17], s[0:1], 0, v[18:19]
	s_waitcnt vmcnt(13)
	v_mov_b32_e32 v2, v72
	v_mov_b32_e32 v3, v73
	v_mov_b32_e32 v4, v74
	v_mov_b32_e32 v5, v75
	v_mov_b32_e32 v6, v76
	v_mov_b32_e32 v7, v77
	v_mov_b32_e32 v8, v78
	v_mov_b32_e32 v9, v79
	v_lshlrev_b32_e32 v23, 16, v2
	v_and_b32_e32 v25, 0xffff0000, v2
	v_lshlrev_b32_e32 v27, 16, v3
	v_lshlrev_b32_e32 v26, 16, v7
	v_and_b32_e32 v3, 0xffff0000, v3
	v_and_b32_e32 v2, 0xffff0000, v7
	v_lshlrev_b32_e32 v7, 16, v4
	v_and_b32_e32 v29, 0xffff0000, v4
	v_lshlrev_b32_e32 v31, 16, v5
	v_and_b32_e32 v5, 0xffff0000, v5
	v_and_b32_e32 v4, 0xffff0000, v9
	v_lshlrev_b32_e32 v22, 16, v6
	v_and_b32_e32 v24, 0xffff0000, v6
	v_lshlrev_b32_e32 v6, 16, v8
	v_and_b32_e32 v28, 0xffff0000, v8
	v_lshlrev_b32_e32 v30, 16, v9
	v_pk_mul_f32 v[2:3], v[10:11], v[2:3]
	v_pk_mul_f32 v[4:5], v[10:11], v[4:5]
	v_pk_mul_f32 v[8:9], v[10:11], v[22:23]
	v_pk_mul_f32 v[22:23], v[10:11], v[24:25]
	v_pk_mul_f32 v[24:25], v[10:11], v[26:27]
	v_pk_mul_f32 v[6:7], v[10:11], v[6:7]
	v_pk_mul_f32 v[26:27], v[10:11], v[28:29]
	v_pk_mul_f32 v[28:29], v[10:11], v[30:31]
	v_fma_f32 v2, v14, v37, v2
	v_fma_f32 v4, v14, v41, v4
	v_fma_f32 v8, v14, v33, v8
	v_fma_f32 v10, v14, v35, v22
	v_fma_f32 v11, v14, v36, v24
	v_fma_f32 v6, v14, v38, v6
	v_fma_f32 v15, v14, v39, v26
	v_fma_f32 v22, v14, v40, v28
	v_add_f32_e32 v3, v2, v3
	v_add_f32_e32 v5, v4, v5
	v_add_f32_e32 v8, v8, v9
	v_add_f32_e32 v9, v10, v23
	v_add_f32_e32 v10, v11, v25
	v_add_f32_e32 v6, v6, v7
	v_add_f32_e32 v7, v15, v27
	v_add_f32_e32 v11, v22, v29
	v_cvt_pk_bf16_f32 v2, v8, v9
	v_cvt_pk_bf16_f32 v3, v10, v3
	v_cvt_pk_bf16_f32 v4, v6, v7
	v_cvt_pk_bf16_f32 v5, v11, v5
	global_store_dwordx4 v[12:13], v[2:5], off
	v_and_b32_e32 v12, -16, v34
	v_mad_u64_u32 v[10:11], s[4:5], v32, s59, v[0:1]
	v_add_u32_e32 v14, s77, v12
	ds_read_b128 v[10:13], v10
	ds_read_b128 v[14:17], v14 offset:8704
	v_add_u32_e32 v33, 0xc0, v198
	v_ashrrev_i32_e32 v34, 4, v33
	v_add_u32_e32 v20, s54, v34
	s_waitcnt lgkmcnt(0)
	v_and_b32_e32 v17, 0x7ff, v20
	v_ashrrev_i32_e32 v20, 11, v20
	v_add3_u32 v20, v20, s35, v17
	v_lshlrev_b32_e32 v32, 16, v10
	v_and_b32_e32 v35, 0xffff0000, v10
	v_lshlrev_b32_e32 v36, 16, v11
	v_and_b32_e32 v37, 0xffff0000, v11
	v_mov_b32_e32 v10, v15
	v_mov_b32_e32 v11, v16
	v_ashrrev_i32_e32 v21, 31, v20
	v_and_b32_e32 v41, 0xffff0000, v13
	v_lshlrev_b64 v[20:21], 12, v[20:21]
	v_lshlrev_b32_e32 v38, 16, v12
	v_and_b32_e32 v39, 0xffff0000, v12
	v_lshlrev_b32_e32 v40, 16, v13
	v_or_b32_e32 v20, v20, v1
	v_lshl_add_u64 v[12:13], s[62:63], 0, v[18:19]
	v_lshl_add_u64 v[18:19], s[64:65], 0, v[20:21]
	v_lshl_add_u64 v[16:17], s[0:1], 0, v[20:21]
	s_waitcnt vmcnt(12)
; #define GAS __attribute__((address_space(1)))
; #define LAS __attribute__((address_space(3)))
; __device__ __forceinline__ void unpack8(const v4u w, float (&f)[8]) { f[0] = bfl(w.x); f[1] = bfh(w.x); f[2] = bfl(w.y); f[3] = bfh(w.y); f[4] = bfl(w.z); f[5] = bfh(w.z); f[6] = bfl(w.w); f[7] = bfh(w.w); }
; __device__ __forceinline__ v4u pack8(const float (&f)[8]) { v4u w; w.x = pk2(f[0], f[1]); w.y = pk2(f[2], f[3]); w.z = pk2(f[4], f[5]); w.w = pk2(f[6], f[7]); return w; }
; template <bool COMBINE>
; __device__ __forceinline__ void attn_phase(Frame& F, const bf16* QKV, bf16* O12, float* LSE, bf16* MO) {
;     ...
;         for (int i = 0; i < 8; ++i) { const int ci = i * 64 + lane, row = ci >> 4, ch = ci & 15;
;             const v4u t = *(const LAS v4u*)(stg + row * SROW + ch * 16);
;             const size_t go = (size_t)tokrow(b, qw0 + row, Lsh) * D + h * 128 + ch * 8;
;             if (!COMBINE) *(GAS v4u*)(O12 + (size_t)(gg - 1) * M * D + go) = t;
;             else { const f32x4 wt = *(const LAS f32x4*)(stg + 32 * SROW + row * 16);
;                 const v4u a = *(const GAS v4u*)(O12 + go), bq = *(const GAS v4u*)(O12 + (size_t)M * D + go);
;                 float f0[8], f1[8], f2[8], r[8]; unpack8(t, f0); unpack8(a, f1); unpack8(bq, f2);
; #pragma unroll
;                 for (int jj = 0; jj < 8; ++jj) r[jj] = wt[0] * f0[jj] + wt[1] * f1[jj] + wt[2] * f2[jj];
;                 *(GAS v4u*)(MO + go) = pack8(r); }
	v_mov_b32_e32 v2, v80
	v_mov_b32_e32 v3, v81
	v_mov_b32_e32 v4, v82
	v_mov_b32_e32 v5, v83
	v_mov_b32_e32 v6, v84
	v_mov_b32_e32 v7, v85
	v_mov_b32_e32 v8, v86
	v_mov_b32_e32 v9, v87
	v_lshlrev_b32_e32 v23, 16, v2
	v_and_b32_e32 v25, 0xffff0000, v2
	v_lshlrev_b32_e32 v27, 16, v3
	v_lshlrev_b32_e32 v26, 16, v7
	v_and_b32_e32 v3, 0xffff0000, v3
	v_and_b32_e32 v2, 0xffff0000, v7
	v_lshlrev_b32_e32 v7, 16, v4
	v_and_b32_e32 v29, 0xffff0000, v4
	v_lshlrev_b32_e32 v31, 16, v5
	v_and_b32_e32 v5, 0xffff0000, v5
	v_and_b32_e32 v4, 0xffff0000, v9
	v_lshlrev_b32_e32 v22, 16, v6
	v_and_b32_e32 v24, 0xffff0000, v6
	v_lshlrev_b32_e32 v6, 16, v8
	v_and_b32_e32 v28, 0xffff0000, v8
	v_lshlrev_b32_e32 v30, 16, v9
	v_pk_mul_f32 v[2:3], v[10:11], v[2:3]
	v_pk_mul_f32 v[4:5], v[10:11], v[4:5]
	v_pk_mul_f32 v[8:9], v[10:11], v[22:23]
	v_pk_mul_f32 v[22:23], v[10:11], v[24:25]
	v_pk_mul_f32 v[24:25], v[10:11], v[26:27]
	v_pk_mul_f32 v[6:7], v[10:11], v[6:7]
	v_pk_mul_f32 v[26:27], v[10:11], v[28:29]
	v_pk_mul_f32 v[28:29], v[10:11], v[30:31]
	v_fma_f32 v2, v14, v37, v2
	v_fma_f32 v4, v14, v41, v4
	v_fma_f32 v8, v14, v32, v8
	v_fma_f32 v10, v14, v35, v22
	v_fma_f32 v11, v14, v36, v24
	v_fma_f32 v6, v14, v38, v6
	v_fma_f32 v15, v14, v39, v26
	v_fma_f32 v22, v14, v40, v28
	v_add_f32_e32 v3, v2, v3
	v_add_f32_e32 v5, v4, v5
	v_add_f32_e32 v8, v8, v9
	v_add_f32_e32 v9, v10, v23
	v_add_f32_e32 v10, v11, v25
	v_add_f32_e32 v6, v6, v7
	v_add_f32_e32 v7, v15, v27
	v_add_f32_e32 v11, v22, v29
	v_cvt_pk_bf16_f32 v2, v8, v9
	v_cvt_pk_bf16_f32 v3, v10, v3
	v_cvt_pk_bf16_f32 v4, v6, v7
	v_cvt_pk_bf16_f32 v5, v11, v5
	global_store_dwordx4 v[12:13], v[2:5], off
	v_and_b32_e32 v12, -16, v33
	v_mad_u64_u32 v[10:11], s[4:5], v34, s59, v[0:1]
	v_add_u32_e32 v14, s77, v12
	ds_read_b128 v[10:13], v10
	ds_read_b128 v[14:17], v14 offset:8704
	v_add_u32_e32 v32, 0x100, v198
	v_ashrrev_i32_e32 v33, 4, v32
	v_add_u32_e32 v18, s54, v33
	s_waitcnt lgkmcnt(0)
	v_and_b32_e32 v17, 0x7ff, v18
	v_ashrrev_i32_e32 v18, 11, v18
	v_add3_u32 v18, v18, s35, v17
	v_lshlrev_b32_e32 v34, 16, v10
	v_and_b32_e32 v35, 0xffff0000, v10
	v_lshlrev_b32_e32 v36, 16, v11
	v_and_b32_e32 v37, 0xffff0000, v11
	v_mov_b32_e32 v10, v15
	v_mov_b32_e32 v11, v16
	v_ashrrev_i32_e32 v19, 31, v18
	v_and_b32_e32 v41, 0xffff0000, v13
	v_lshlrev_b64 v[18:19], 12, v[18:19]
	v_lshlrev_b32_e32 v38, 16, v12
	v_and_b32_e32 v39, 0xffff0000, v12
	v_lshlrev_b32_e32 v40, 16, v13
	v_or_b32_e32 v18, v18, v1
	v_lshl_add_u64 v[12:13], s[62:63], 0, v[20:21]
	v_lshl_add_u64 v[20:21], s[64:65], 0, v[18:19]
	v_lshl_add_u64 v[16:17], s[0:1], 0, v[18:19]
	s_waitcnt vmcnt(11)
	v_mov_b32_e32 v2, v88
	v_mov_b32_e32 v3, v89
	v_mov_b32_e32 v4, v90
	v_mov_b32_e32 v5, v91
	v_mov_b32_e32 v6, v92
	v_mov_b32_e32 v7, v93
	v_mov_b32_e32 v8, v94
	v_mov_b32_e32 v9, v95
	v_lshlrev_b32_e32 v23, 16, v2
	v_and_b32_e32 v25, 0xffff0000, v2
	v_lshlrev_b32_e32 v27, 16, v3
	v_lshlrev_b32_e32 v26, 16, v7
	v_and_b32_e32 v3, 0xffff0000, v3
	v_and_b32_e32 v2, 0xffff0000, v7
	v_lshlrev_b32_e32 v7, 16, v4
	v_and_b32_e32 v29, 0xffff0000, v4
	v_lshlrev_b32_e32 v31, 16, v5
	v_and_b32_e32 v5, 0xffff0000, v5
	v_and_b32_e32 v4, 0xffff0000, v9
	v_lshlrev_b32_e32 v22, 16, v6
	v_and_b32_e32 v24, 0xffff0000, v6
	v_lshlrev_b32_e32 v6, 16, v8
	v_and_b32_e32 v28, 0xffff0000, v8
	v_lshlrev_b32_e32 v30, 16, v9
	v_pk_mul_f32 v[2:3], v[10:11], v[2:3]
	v_pk_mul_f32 v[4:5], v[10:11], v[4:5]
	v_pk_mul_f32 v[8:9], v[10:11], v[22:23]
	v_pk_mul_f32 v[22:23], v[10:11], v[24:25]
	v_pk_mul_f32 v[24:25], v[10:11], v[26:27]
	v_pk_mul_f32 v[6:7], v[10:11], v[6:7]
	v_pk_mul_f32 v[26:27], v[10:11], v[28:29]
	v_pk_mul_f32 v[28:29], v[10:11], v[30:31]
	v_fma_f32 v2, v14, v37, v2
	v_fma_f32 v4, v14, v41, v4
	v_fma_f32 v8, v14, v34, v8
	v_fma_f32 v10, v14, v35, v22
	v_fma_f32 v11, v14, v36, v24
	v_fma_f32 v6, v14, v38, v6
	v_fma_f32 v15, v14, v39, v26
	v_fma_f32 v22, v14, v40, v28
	v_add_f32_e32 v3, v2, v3
	v_add_f32_e32 v5, v4, v5
	v_add_f32_e32 v8, v8, v9
	v_add_f32_e32 v9, v10, v23
	v_add_f32_e32 v10, v11, v25
	v_add_f32_e32 v6, v6, v7
	v_add_f32_e32 v7, v15, v27
	v_add_f32_e32 v11, v22, v29
	v_cvt_pk_bf16_f32 v2, v8, v9
	v_cvt_pk_bf16_f32 v3, v10, v3
	v_cvt_pk_bf16_f32 v4, v6, v7
	v_cvt_pk_bf16_f32 v5, v11, v5
	global_store_dwordx4 v[12:13], v[2:5], off
	v_and_b32_e32 v12, -16, v32
	v_mad_u64_u32 v[10:11], s[4:5], v33, s59, v[0:1]
	v_add_u32_e32 v14, s77, v12
	ds_read_b128 v[10:13], v10
	ds_read_b128 v[14:17], v14 offset:8704
	v_add_u32_e32 v34, 0x140, v198
	v_ashrrev_i32_e32 v32, 4, v34
	v_add_u32_e32 v20, s54, v32
	s_waitcnt lgkmcnt(0)
	v_and_b32_e32 v17, 0x7ff, v20
	v_ashrrev_i32_e32 v20, 11, v20
	v_add3_u32 v20, v20, s35, v17
	v_lshlrev_b32_e32 v33, 16, v10
	v_and_b32_e32 v35, 0xffff0000, v10
	v_lshlrev_b32_e32 v36, 16, v11
	v_and_b32_e32 v37, 0xffff0000, v11
	v_mov_b32_e32 v10, v15
	v_mov_b32_e32 v11, v16
	v_ashrrev_i32_e32 v21, 31, v20
	v_and_b32_e32 v41, 0xffff0000, v13
	v_lshlrev_b64 v[20:21], 12, v[20:21]
	v_lshlrev_b32_e32 v38, 16, v12
	v_and_b32_e32 v39, 0xffff0000, v12
	v_lshlrev_b32_e32 v40, 16, v13
	v_or_b32_e32 v20, v20, v1
	v_lshl_add_u64 v[12:13], s[62:63], 0, v[18:19]
	v_lshl_add_u64 v[18:19], s[64:65], 0, v[20:21]
	v_lshl_add_u64 v[16:17], s[0:1], 0, v[20:21]
	s_waitcnt vmcnt(10)
; #define GAS __attribute__((address_space(1)))
; #define LAS __attribute__((address_space(3)))
; __device__ __forceinline__ void unpack8(const v4u w, float (&f)[8]) { f[0] = bfl(w.x); f[1] = bfh(w.x); f[2] = bfl(w.y); f[3] = bfh(w.y); f[4] = bfl(w.z); f[5] = bfh(w.z); f[6] = bfl(w.w); f[7] = bfh(w.w); }
; __device__ __forceinline__ v4u pack8(const float (&f)[8]) { v4u w; w.x = pk2(f[0], f[1]); w.y = pk2(f[2], f[3]); w.z = pk2(f[4], f[5]); w.w = pk2(f[6], f[7]); return w; }
; template <bool COMBINE>
; __device__ __forceinline__ void attn_phase(Frame& F, const bf16* QKV, bf16* O12, float* LSE, bf16* MO) {
;     ...
;         for (int i = 0; i < 8; ++i) { const int ci = i * 64 + lane, row = ci >> 4, ch = ci & 15;
;             const v4u t = *(const LAS v4u*)(stg + row * SROW + ch * 16);
;             const size_t go = (size_t)tokrow(b, qw0 + row, Lsh) * D + h * 128 + ch * 8;
;             if (!COMBINE) *(GAS v4u*)(O12 + (size_t)(gg - 1) * M * D + go) = t;
;             else { const f32x4 wt = *(const LAS f32x4*)(stg + 32 * SROW + row * 16);
;                 const v4u a = *(const GAS v4u*)(O12 + go), bq = *(const GAS v4u*)(O12 + (size_t)M * D + go);
;                 float f0[8], f1[8], f2[8], r[8]; unpack8(t, f0); unpack8(a, f1); unpack8(bq, f2);
; #pragma unroll
;                 for (int jj = 0; jj < 8; ++jj) r[jj] = wt[0] * f0[jj] + wt[1] * f1[jj] + wt[2] * f2[jj];
;                 *(GAS v4u*)(MO + go) = pack8(r); }
	v_mov_b32_e32 v2, v96
	v_mov_b32_e32 v3, v97
	v_mov_b32_e32 v4, v98
	v_mov_b32_e32 v5, v99
	v_mov_b32_e32 v6, v100
	v_mov_b32_e32 v7, v101
	v_mov_b32_e32 v8, v102
	v_mov_b32_e32 v9, v103
	v_lshlrev_b32_e32 v23, 16, v2
	v_and_b32_e32 v25, 0xffff0000, v2
	v_lshlrev_b32_e32 v27, 16, v3
	v_lshlrev_b32_e32 v26, 16, v7
	v_and_b32_e32 v3, 0xffff0000, v3
	v_and_b32_e32 v2, 0xffff0000, v7
	v_lshlrev_b32_e32 v7, 16, v4
	v_and_b32_e32 v29, 0xffff0000, v4
	v_lshlrev_b32_e32 v31, 16, v5
	v_and_b32_e32 v5, 0xffff0000, v5
	v_and_b32_e32 v4, 0xffff0000, v9
	v_lshlrev_b32_e32 v22, 16, v6
	v_and_b32_e32 v24, 0xffff0000, v6
	v_lshlrev_b32_e32 v6, 16, v8
	v_and_b32_e32 v28, 0xffff0000, v8
	v_lshlrev_b32_e32 v30, 16, v9
	v_pk_mul_f32 v[2:3], v[10:11], v[2:3]
	v_pk_mul_f32 v[4:5], v[10:11], v[4:5]
	v_pk_mul_f32 v[8:9], v[10:11], v[22:23]
	v_pk_mul_f32 v[22:23], v[10:11], v[24:25]
	v_pk_mul_f32 v[24:25], v[10:11], v[26:27]
	v_pk_mul_f32 v[6:7], v[10:11], v[6:7]
	v_pk_mul_f32 v[26:27], v[10:11], v[28:29]
	v_pk_mul_f32 v[28:29], v[10:11], v[30:31]
	v_fma_f32 v2, v14, v37, v2
	v_fma_f32 v4, v14, v41, v4
	v_fma_f32 v8, v14, v33, v8
	v_fma_f32 v10, v14, v35, v22
	v_fma_f32 v11, v14, v36, v24
	v_fma_f32 v6, v14, v38, v6
	v_fma_f32 v15, v14, v39, v26
	v_fma_f32 v22, v14, v40, v28
	v_add_f32_e32 v3, v2, v3
	v_add_f32_e32 v5, v4, v5
	v_add_f32_e32 v8, v8, v9
	v_add_f32_e32 v9, v10, v23
	v_add_f32_e32 v10, v11, v25
	v_add_f32_e32 v6, v6, v7
	v_add_f32_e32 v7, v15, v27
	v_add_f32_e32 v11, v22, v29
	v_cvt_pk_bf16_f32 v2, v8, v9
	v_cvt_pk_bf16_f32 v3, v10, v3
	v_cvt_pk_bf16_f32 v4, v6, v7
	v_cvt_pk_bf16_f32 v5, v11, v5
	global_store_dwordx4 v[12:13], v[2:5], off
	v_and_b32_e32 v12, -16, v34
	v_mad_u64_u32 v[10:11], s[4:5], v32, s59, v[0:1]
	v_add_u32_e32 v14, s77, v12
	ds_read_b128 v[10:13], v10
	ds_read_b128 v[14:17], v14 offset:8704
	v_add_u32_e32 v33, 0x180, v198
	v_ashrrev_i32_e32 v34, 4, v33
	v_add_u32_e32 v18, s54, v34
	s_waitcnt lgkmcnt(0)
	v_and_b32_e32 v17, 0x7ff, v18
	v_ashrrev_i32_e32 v18, 11, v18
	v_add3_u32 v18, v18, s35, v17
	v_lshlrev_b32_e32 v32, 16, v10
	v_and_b32_e32 v35, 0xffff0000, v10
	v_lshlrev_b32_e32 v36, 16, v11
	v_and_b32_e32 v37, 0xffff0000, v11
	v_mov_b32_e32 v10, v15
	v_mov_b32_e32 v11, v16
	v_ashrrev_i32_e32 v19, 31, v18
	v_and_b32_e32 v41, 0xffff0000, v13
	v_lshlrev_b64 v[18:19], 12, v[18:19]
	v_lshlrev_b32_e32 v38, 16, v12
	v_and_b32_e32 v39, 0xffff0000, v12
	v_lshlrev_b32_e32 v40, 16, v13
	v_or_b32_e32 v18, v18, v1
	v_lshl_add_u64 v[12:13], s[62:63], 0, v[20:21]
	v_lshl_add_u64 v[20:21], s[64:65], 0, v[18:19]
	v_lshl_add_u64 v[16:17], s[0:1], 0, v[18:19]
	s_waitcnt vmcnt(9)
	v_mov_b32_e32 v2, v104
	v_mov_b32_e32 v3, v105
	v_mov_b32_e32 v4, v106
	v_mov_b32_e32 v5, v107
	v_mov_b32_e32 v6, v108
	v_mov_b32_e32 v7, v109
	v_mov_b32_e32 v8, v110
	v_mov_b32_e32 v9, v111
	v_lshlrev_b32_e32 v23, 16, v2
	v_and_b32_e32 v25, 0xffff0000, v2
	v_lshlrev_b32_e32 v27, 16, v3
	v_lshlrev_b32_e32 v26, 16, v7
	v_and_b32_e32 v3, 0xffff0000, v3
	v_and_b32_e32 v2, 0xffff0000, v7
	v_lshlrev_b32_e32 v7, 16, v4
	v_and_b32_e32 v29, 0xffff0000, v4
	v_lshlrev_b32_e32 v31, 16, v5
	v_and_b32_e32 v5, 0xffff0000, v5
	v_and_b32_e32 v4, 0xffff0000, v9
	v_lshlrev_b32_e32 v22, 16, v6
	v_and_b32_e32 v24, 0xffff0000, v6
	v_lshlrev_b32_e32 v6, 16, v8
	v_and_b32_e32 v28, 0xffff0000, v8
	v_lshlrev_b32_e32 v30, 16, v9
	v_pk_mul_f32 v[2:3], v[10:11], v[2:3]
	v_pk_mul_f32 v[4:5], v[10:11], v[4:5]
	v_pk_mul_f32 v[8:9], v[10:11], v[22:23]
	v_pk_mul_f32 v[22:23], v[10:11], v[24:25]
	v_pk_mul_f32 v[24:25], v[10:11], v[26:27]
	v_pk_mul_f32 v[6:7], v[10:11], v[6:7]
	v_pk_mul_f32 v[26:27], v[10:11], v[28:29]
	v_pk_mul_f32 v[28:29], v[10:11], v[30:31]
	v_fma_f32 v2, v14, v37, v2
	v_fma_f32 v4, v14, v41, v4
	v_fma_f32 v8, v14, v32, v8
	v_fma_f32 v10, v14, v35, v22
	v_fma_f32 v11, v14, v36, v24
	v_fma_f32 v6, v14, v38, v6
	v_fma_f32 v15, v14, v39, v26
	v_fma_f32 v22, v14, v40, v28
	v_add_f32_e32 v3, v2, v3
	v_add_f32_e32 v5, v4, v5
	v_add_f32_e32 v8, v8, v9
	v_add_f32_e32 v9, v10, v23
	v_add_f32_e32 v10, v11, v25
	v_add_f32_e32 v6, v6, v7
	v_add_f32_e32 v7, v15, v27
	v_add_f32_e32 v11, v22, v29
	v_cvt_pk_bf16_f32 v2, v8, v9
	v_cvt_pk_bf16_f32 v3, v10, v3
	v_cvt_pk_bf16_f32 v4, v6, v7
	v_cvt_pk_bf16_f32 v5, v11, v5
	global_store_dwordx4 v[12:13], v[2:5], off
	v_add_u32_e32 v32, 0x1c0, v198
	v_and_b32_e32 v12, -16, v33
	v_ashrrev_i32_e32 v33, 4, v32
	v_mad_u64_u32 v[10:11], s[4:5], v34, s59, v[0:1]
	v_add_u32_e32 v14, s77, v12
	v_add_u32_e32 v20, s54, v33
	ds_read_b128 v[10:13], v10
	ds_read_b128 v[14:17], v14 offset:8704
	s_waitcnt lgkmcnt(0)
	v_and_b32_e32 v17, 0x7ff, v20
	v_ashrrev_i32_e32 v20, 11, v20
	v_add3_u32 v20, v20, s35, v17
	v_ashrrev_i32_e32 v21, 31, v20
	v_lshlrev_b64 v[20:21], 12, v[20:21]
	v_or_b32_e32 v20, v20, v1
	v_lshlrev_b32_e32 v1, 16, v10
	v_and_b32_e32 v34, 0xffff0000, v10
	v_lshlrev_b32_e32 v35, 16, v11
	v_and_b32_e32 v36, 0xffff0000, v11
	v_mov_b32_e32 v10, v15
	v_mov_b32_e32 v11, v16
	v_and_b32_e32 v40, 0xffff0000, v13
	v_lshlrev_b32_e32 v37, 16, v12
	v_and_b32_e32 v38, 0xffff0000, v12
	v_lshlrev_b32_e32 v39, 16, v13
	v_lshl_add_u64 v[12:13], s[62:63], 0, v[18:19]
	v_lshl_add_u64 v[18:19], s[64:65], 0, v[20:21]
	v_lshl_add_u64 v[16:17], s[0:1], 0, v[20:21]
	s_waitcnt vmcnt(8)
; #define GAS __attribute__((address_space(1)))
; #define LAS __attribute__((address_space(3)))
;     __device__ __forceinline__ void ids() { lane = fresh_lane(); tid = wave * 64 + lane; }
; __device__ __forceinline__ void unpack8(const v4u w, float (&f)[8]) { f[0] = bfl(w.x); f[1] = bfh(w.x); f[2] = bfl(w.y); f[3] = bfh(w.y); f[4] = bfl(w.z); f[5] = bfh(w.z); f[6] = bfl(w.w); f[7] = bfh(w.w); }
; template <bool COMBINE>
; __device__ __forceinline__ void attn_phase(Frame& F, const bf16* QKV, bf16* O12, float* LSE, bf16* MO) {
;     ...
;         F.ids();
;         const int lane = F.lane, ql = lane & 31, hh = lane >> 5;
;         const int qblk = u & 7, h = (u >> 3) & 15, rest = u >> 7;
;         const int gg = COMBINE ? 0 : 1 + (rest & 1), b = COMBINE ? rest : (rest >> 1);
;         const int Lsh = gg == 0 ? 11 : (gg == 1 ? 9 : 7);
;         const int q0 = qblk * 256, cs0 = (q0 >> Lsh) << Lsh, kv0 = (q0 - 128) > cs0 ? (q0 - 128) : cs0;
;         const bf16* Qp = QKV + (size_t)gg * 6144 + h * 128; const bf16* Kp = Qp + 2048; const bf16* Vp = Qp + 4096;
;         const int qw0 = q0 + 32 * F.wave, cs = (qw0 >> Lsh) << Lsh;
;         const int qrow = tokrow(b, qw0 + ql, Lsh);
;         v4u vst[12];
;         const int nvp = (q0 + 256 - kv0) * 16;
; #pragma unroll
;         for (int j = 0; j < 12; ++j) { const int i = F.tid + j * NTHR; vst[j] = (v4u){0u, 0u, 0u, 0u};
;             if (i < nvp) vst[j] = *(const GAS v4u*)(Vp + (size_t)tokrow(b, kv0 + (i >> 4), Lsh) * NQKV + (i & 15) * 8); }
;     ...
;         for (int i = 0; i < 8; ++i) { const int ci = i * 64 + lane, row = ci >> 4, ch = ci & 15;
;             const v4u t = *(const LAS v4u*)(stg + row * SROW + ch * 16);
;             const size_t go = (size_t)tokrow(b, qw0 + row, Lsh) * D + h * 128 + ch * 8;
;             if (!COMBINE) *(GAS v4u*)(O12 + (size_t)(gg - 1) * M * D + go) = t;
;             else { const f32x4 wt = *(const LAS f32x4*)(stg + 32 * SROW + row * 16);
;                 const v4u a = *(const GAS v4u*)(O12 + go), bq = *(const GAS v4u*)(O12 + (size_t)M * D + go);
;                 float f0[8], f1[8], f2[8], r[8]; unpack8(t, f0); unpack8(a, f1); unpack8(bq, f2);
; #pragma unroll
;                 for (int jj = 0; jj < 8; ++jj) r[jj] = wt[0] * f0[jj] + wt[1] * f1[jj] + wt[2] * f2[jj];
;                 *(GAS v4u*)(MO + go) = pack8(r); }
;         }
	v_mov_b32_e32 v2, v112
	v_mov_b32_e32 v3, v113
	v_mov_b32_e32 v4, v114
	v_mov_b32_e32 v5, v115
	v_mov_b32_e32 v6, v116
	v_mov_b32_e32 v7, v117
	v_mov_b32_e32 v8, v118
	v_mov_b32_e32 v9, v119
	v_lshlrev_b32_e32 v23, 16, v2
	v_and_b32_e32 v25, 0xffff0000, v2
	v_lshlrev_b32_e32 v27, 16, v3
	v_lshlrev_b32_e32 v26, 16, v7
	v_and_b32_e32 v3, 0xffff0000, v3
	v_and_b32_e32 v2, 0xffff0000, v7
	v_lshlrev_b32_e32 v7, 16, v4
	v_and_b32_e32 v29, 0xffff0000, v4
	v_lshlrev_b32_e32 v31, 16, v5
	v_and_b32_e32 v5, 0xffff0000, v5
	v_and_b32_e32 v4, 0xffff0000, v9
	v_lshlrev_b32_e32 v22, 16, v6
	v_and_b32_e32 v24, 0xffff0000, v6
	v_lshlrev_b32_e32 v6, 16, v8
	v_and_b32_e32 v28, 0xffff0000, v8
	v_lshlrev_b32_e32 v30, 16, v9
	v_pk_mul_f32 v[2:3], v[10:11], v[2:3]
	v_pk_mul_f32 v[4:5], v[10:11], v[4:5]
	v_pk_mul_f32 v[8:9], v[10:11], v[22:23]
	v_pk_mul_f32 v[22:23], v[10:11], v[24:25]
	v_pk_mul_f32 v[24:25], v[10:11], v[26:27]
	v_pk_mul_f32 v[6:7], v[10:11], v[6:7]
	v_pk_mul_f32 v[26:27], v[10:11], v[28:29]
	v_pk_mul_f32 v[28:29], v[10:11], v[30:31]
	v_fma_f32 v2, v14, v36, v2
	v_fma_f32 v4, v14, v40, v4
	v_fma_f32 v1, v14, v1, v8
	v_fma_f32 v8, v14, v34, v22
	v_fma_f32 v10, v14, v35, v24
	v_fma_f32 v6, v14, v37, v6
	v_fma_f32 v11, v14, v38, v26
	v_fma_f32 v15, v14, v39, v28
	v_add_f32_e32 v3, v2, v3
	v_add_f32_e32 v5, v4, v5
	v_add_f32_e32 v1, v1, v9
	v_add_f32_e32 v8, v8, v23
	v_add_f32_e32 v9, v10, v25
	v_add_f32_e32 v6, v6, v7
	v_add_f32_e32 v7, v11, v27
	v_add_f32_e32 v10, v15, v29
	v_cvt_pk_bf16_f32 v2, v1, v8
	v_cvt_pk_bf16_f32 v3, v9, v3
	v_cvt_pk_bf16_f32 v4, v6, v7
	v_cvt_pk_bf16_f32 v5, v10, v5
	global_store_dwordx4 v[12:13], v[2:5], off
	v_mad_u64_u32 v[0:1], s[4:5], v33, s59, v[0:1]
	ds_read_b128 v[10:13], v0
	v_and_b32_e32 v0, -16, v32
	v_add_u32_e32 v0, s77, v0
	ds_read_b128 v[14:17], v0 offset:8704
	s_waitcnt lgkmcnt(1)
	v_lshlrev_b32_e32 v28, 16, v12
	v_and_b32_e32 v29, 0xffff0000, v12
	v_lshlrev_b32_e32 v30, 16, v13
	v_and_b32_e32 v31, 0xffff0000, v13
	s_waitcnt lgkmcnt(0)
	v_mov_b32_e32 v0, v15
	v_mov_b32_e32 v1, v16
	v_lshlrev_b32_e32 v24, 16, v10
	v_and_b32_e32 v25, 0xffff0000, v10
	v_lshlrev_b32_e32 v26, 16, v11
	v_and_b32_e32 v27, 0xffff0000, v11
	v_lshl_add_u64 v[10:11], s[62:63], 0, v[20:21]
	s_waitcnt vmcnt(7)
	v_mov_b32_e32 v2, v120
	v_mov_b32_e32 v3, v121
	v_mov_b32_e32 v4, v122
	v_mov_b32_e32 v5, v123
	v_mov_b32_e32 v6, v124
	v_mov_b32_e32 v7, v125
	v_mov_b32_e32 v8, v126
	v_mov_b32_e32 v9, v127
	v_lshlrev_b32_e32 v13, 16, v2
	v_lshlrev_b32_e32 v12, 16, v6
	v_and_b32_e32 v17, 0xffff0000, v2
	v_and_b32_e32 v16, 0xffff0000, v6
	v_lshlrev_b32_e32 v19, 16, v3
	v_lshlrev_b32_e32 v18, 16, v7
	v_and_b32_e32 v3, 0xffff0000, v3
	v_and_b32_e32 v2, 0xffff0000, v7
	v_lshlrev_b32_e32 v7, 16, v4
	v_lshlrev_b32_e32 v6, 16, v8
	v_and_b32_e32 v21, 0xffff0000, v4
	v_and_b32_e32 v20, 0xffff0000, v8
	v_lshlrev_b32_e32 v23, 16, v5
	v_lshlrev_b32_e32 v22, 16, v9
	v_and_b32_e32 v5, 0xffff0000, v5
	v_and_b32_e32 v4, 0xffff0000, v9
	v_pk_mul_f32 v[2:3], v[0:1], v[2:3]
	v_pk_mul_f32 v[6:7], v[0:1], v[6:7]
	v_pk_mul_f32 v[8:9], v[0:1], v[12:13]
	v_pk_mul_f32 v[12:13], v[0:1], v[16:17]
	v_pk_mul_f32 v[16:17], v[0:1], v[18:19]
	v_pk_mul_f32 v[18:19], v[0:1], v[20:21]
	v_pk_mul_f32 v[20:21], v[0:1], v[22:23]
	v_pk_mul_f32 v[0:1], v[0:1], v[4:5]
	v_fma_f32 v2, v14, v27, v2
	v_fma_f32 v6, v14, v28, v6
	v_fma_f32 v4, v14, v24, v8
	v_fma_f32 v5, v14, v25, v12
	v_fma_f32 v8, v14, v26, v16
	v_fma_f32 v12, v14, v29, v18
	v_fma_f32 v15, v14, v30, v20
	v_fma_f32 v0, v14, v31, v0
	v_add_f32_e32 v2, v2, v3
	v_add_f32_e32 v3, v6, v7
	v_add_f32_e32 v4, v4, v9
	v_add_f32_e32 v5, v5, v13
	v_add_f32_e32 v8, v8, v17
	v_add_f32_e32 v6, v12, v19
	v_add_f32_e32 v7, v15, v21
	v_add_f32_e32 v9, v0, v1
	v_cvt_pk_bf16_f32 v0, v4, v5
	v_cvt_pk_bf16_f32 v1, v8, v2
	v_cvt_pk_bf16_f32 v2, v3, v6
	v_cvt_pk_bf16_f32 v3, v7, v9
	global_store_dwordx4 v[10:11], v[0:3], off
	s_cbranch_scc0 .LBB0_3643
.LBB0_3562:
	s_bfe_u32 s33, s34, 0x40003
	s_and_b32 s37, s80, 0x700
	s_max_u32 s46, s37, 0x80
	s_lshl_b32 s4, s33, 8
	s_add_u32 s10, s3, s4
	v_mbcnt_lo_u32_b32 v198, -1, 0
	v_mbcnt_hi_u32_b32 v198, -1, v198
	s_addc_u32 s11, s53, 0
	s_sub_i32 s4, s37, s46
	v_lshlrev_b32_e32 v0, 4, v198
	s_lshl_b32 s30, s4, 4
	v_and_b32_e32 v188, 0xf0, v0
	v_add_u32_e32 v176, s73, v198
	s_addk_i32 s30, 0x1800
	v_lshl_add_u64 v[0:1], s[10:11], 0, v[188:189]
	v_sub_u32_e64 v2, s37, v194 clamp
	s_and_b32 s35, s78, 0xfffff800
	v_lshl_add_u64 v[0:1], v[0:1], 0, s[66:67]
	v_cmp_gt_i32_e64 s[4:5], s30, v176
	s_waitcnt vmcnt(7)
	v_mov_b32_e32 v20, 0
	v_mov_b32_e32 v21, 0
	v_mov_b32_e32 v22, 0
	v_mov_b32_e32 v23, 0
	s_and_saveexec_b64 s[6:7], s[4:5]
	s_cbranch_execz .LBB0_3564
	v_ashrrev_i32_e32 v3, 4, v176
	v_add_u32_e32 v3, v2, v3
	v_and_b32_e32 v4, 0x7ff, v3
	v_ashrrev_i32_e32 v3, 11, v3
	v_add3_u32 v3, v3, s35, v4
	v_mad_i64_i32 v[4:5], s[8:9], v3, s82, v[0:1]
	global_load_dwordx4 v[20:23], v[4:5], off
